# hazard-clean rebuild: padding restored where instructions were removed (s_nop at deleted waits; 2 wait states before the MFMA that follows the P pack)
# speedup vs baseline: 1.0024x; 1.0014x over previous
.LBB0_423:
	v_add_u32_e32 v81, s5, v206
	ds_read_b128 v[82:85], v81
	ds_read_b128 v[86:89], v81 offset:4096
	v_add_u32_e32 v90, s5, v207
	v_add_u32_e32 v94, s5, v208
	v_exp_f32_e32 v128, v128
	v_exp_f32_e32 v129, v129
	v_exp_f32_e32 v152, v96
	v_exp_f32_e32 v153, v97
	v_add_u32_e32 v81, s5, v209
	s_waitcnt lgkmcnt(1)
	v_mfma_f32_32x32x16_bf16 v[112:127], v[82:85], v[160:163], v[64:79]
	ds_read_b128 v[82:85], v90
	ds_read_b128 v[90:93], v90 offset:4096
	ds_read_b128 v[144:147], v94
	ds_read_b128 v[148:151], v94 offset:4096
	v_add_f32_e32 v154, v153, v152
	v_exp_f32_e32 v108, v108
	v_exp_f32_e32 v109, v109
	v_exp_f32_e32 v110, v110
	v_exp_f32_e32 v111, v111
	s_add_i32 s4, s4, 2
	s_waitcnt lgkmcnt(4)
	v_mfma_f32_32x32x16_bf16 v[216:231], v[86:89], v[160:163], v[64:79]
	ds_read_b128 v[86:89], v81
	ds_read_b128 v[94:97], v81 offset:4096
	v_add_f32_e32 v81, v129, v128
	v_add_f32_e32 v81, v154, v81
	v_add_f32_e32 v81, 0, v81
	v_cvt_pk_bf16_f32 v128, v128, v129
	s_add_i32 s5, s76, s77
	s_cmpk_eq_i32 s5, 0x2000
	s_waitcnt lgkmcnt(5)
	v_mfma_f32_32x32x16_bf16 v[112:127], v[82:85], v[164:167], v[112:127]
	v_exp_f32_e32 v83, v130
	v_exp_f32_e32 v84, v131
	v_exp_f32_e32 v85, v98
	v_exp_f32_e32 v98, v99
	v_exp_f32_e32 v99, v103
	v_cvt_pk_bf16_f32 v129, v83, v84
	v_exp_f32_e32 v103, v137
	s_waitcnt lgkmcnt(4)
	v_mfma_f32_32x32x16_bf16 v[216:231], v[90:93], v[164:167], v[216:231]
	v_add_f32_e32 v90, v84, v83
	v_add_f32_e32 v91, v98, v85
	v_add_f32_e32 v90, v91, v90
	v_add_f32_e32 v81, v90, v81
	v_exp_f32_e32 v90, v132
	v_exp_f32_e32 v91, v133
	v_exp_f32_e32 v92, v100
	v_exp_f32_e32 v93, v101
	s_waitcnt lgkmcnt(3)
	v_mfma_f32_32x32x16_bf16 v[112:127], v[144:147], v[168:171], v[112:127]
	v_cvt_pk_bf16_f32 v83, v85, v98
	v_add_f32_e32 v84, v91, v90
	v_add_f32_e32 v85, v93, v92
	v_add_f32_e32 v84, v85, v84
	v_cvt_pk_bf16_f32 v130, v90, v91
	v_exp_f32_e32 v85, v134
	v_exp_f32_e32 v90, v135
	s_waitcnt lgkmcnt(2)
	v_mfma_f32_32x32x16_bf16 v[216:231], v[148:151], v[168:171], v[216:231]
	v_exp_f32_e32 v98, v102
	v_add_f32_e32 v81, v84, v81
	v_add_f32_e32 v91, v90, v85
	v_exp_f32_e32 v102, v136
	v_exp_f32_e32 v136, v104
	v_exp_f32_e32 v137, v105
	v_cvt_pk_bf16_f32 v84, v92, v93
	s_waitcnt lgkmcnt(1)
	v_mfma_f32_32x32x16_bf16 v[112:127], v[86:89], v[172:175], v[112:127]
	v_add_f32_e32 v86, v99, v98
	v_add_f32_e32 v86, v86, v91
	v_add_f32_e32 v81, v86, v81
	ds_read_b64_tr_b16 v[86:87], v213 offset:40960
	ds_read_b64_tr_b16 v[88:89], v213 offset:43008
	v_cvt_pk_bf16_f32 v131, v85, v90
	v_add_f32_e32 v104, v103, v102
	v_add_f32_e32 v105, v137, v136
	s_waitcnt lgkmcnt(2)
	v_mfma_f32_32x32x16_bf16 v[216:231], v[94:97], v[172:175], v[216:231]
	ds_read_b64_tr_b16 v[90:91], v214 offset:40960
	ds_read_b64_tr_b16 v[92:93], v214 offset:43008
	ds_read_b64_tr_b16 v[94:95], v213 offset:45056
	ds_read_b64_tr_b16 v[96:97], v213 offset:47104
	v_cvt_pk_bf16_f32 v85, v98, v99
	v_cvt_pk_bf16_f32 v82, v152, v153
	s_cselect_b32 s8, s71, 0x2000
	s_cmpk_lg_i32 s5, 0x6000
	s_cselect_b32 s77, s8, 0
	s_add_u32 s38, s38, 0x40000
	s_waitcnt lgkmcnt(2)
	v_mfma_f32_32x32x16_bf16 v[32:47], v[90:93], v[128:131], v[32:47]
	v_add_f32_e32 v90, v105, v104
	v_add_f32_e32 v81, v90, v81
	v_cvt_pk_bf16_f32 v90, v102, v103
	v_exp_f32_e32 v91, v138
	v_exp_f32_e32 v92, v139
	v_exp_f32_e32 v138, v106
	v_exp_f32_e32 v106, v140
	v_mfma_f32_32x32x16_bf16 v[48:63], v[86:89], v[128:131], v[48:63]
	ds_read_b64_tr_b16 v[86:87], v215 offset:40960
	ds_read_b64_tr_b16 v[88:89], v215 offset:43008
	ds_read_b64_tr_b16 v[98:99], v214 offset:45056
	ds_read_b64_tr_b16 v[100:101], v214 offset:47104
	ds_read_b64_tr_b16 v[102:103], v248 offset:40960
	ds_read_b64_tr_b16 v[104:105], v248 offset:43008
	ds_read_b64_tr_b16 v[132:133], v215 offset:45056
	ds_read_b64_tr_b16 v[134:135], v215 offset:47104
	v_exp_f32_e32 v139, v107
	v_mov_b64_e32 v[158:159], v[230:231]
	s_addc_u32 s39, s39, 0
	s_add_i32 s75, s75, 0x20000
	s_and_b64 vcc, exec, s[6:7]
	s_waitcnt lgkmcnt(2)
	v_mfma_f32_32x32x16_bf16 v[0:15], v[102:105], v[128:131], v[0:15]
	v_exp_f32_e32 v102, v141
	v_exp_f32_e32 v103, v142
	v_exp_f32_e32 v104, v143
	v_add_f32_e32 v105, v92, v91
	v_cvt_pk_bf16_f32 v91, v91, v92
	v_cvt_pk_bf16_f32 v92, v106, v102
	v_cvt_pk_bf16_f32 v93, v103, v104
	v_mfma_f32_32x32x16_bf16 v[16:31], v[86:89], v[128:131], v[16:31]
	ds_read_b64_tr_b16 v[86:87], v248 offset:45056
	ds_read_b64_tr_b16 v[88:89], v248 offset:47104
	v_mov_b64_e32 v[156:157], v[228:229]
	v_mov_b64_e32 v[154:155], v[226:227]
	v_mov_b64_e32 v[152:153], v[224:225]
	v_mov_b64_e32 v[150:151], v[222:223]
	v_mov_b64_e32 v[148:149], v[220:221]
	v_mov_b64_e32 v[146:147], v[218:219]
	v_mfma_f32_32x32x16_bf16 v[48:63], v[94:97], v[90:93], v[48:63]
	v_add_f32_e32 v94, v139, v138
	v_add_f32_e32 v94, v94, v105
	v_add_f32_e32 v81, v94, v81
	v_add_f32_e32 v94, v102, v106
	v_add_f32_e32 v95, v109, v108
	v_add_f32_e32 v94, v95, v94
	v_add_f32_e32 v81, v94, v81
	v_mfma_f32_32x32x16_bf16 v[32:47], v[98:101], v[90:93], v[32:47]
	v_add_f32_e32 v94, v104, v103
	v_add_f32_e32 v95, v111, v110
	v_add_f32_e32 v94, v95, v94
	v_add_f32_e32 v106, v94, v81
	v_max_f32_e32 v81, v113, v113
	v_max_f32_e32 v94, v112, v112
	v_max_f32_e32 v81, v94, v81
	s_waitcnt lgkmcnt(2)
	v_mfma_f32_32x32x16_bf16 v[16:31], v[132:135], v[90:93], v[16:31]
	ds_read_b64_tr_b16 v[94:95], v213 offset:49152
	ds_read_b64_tr_b16 v[96:97], v213 offset:51200
	v_max3_f32 v81, v81, v114, v115
	v_max3_f32 v81, v81, v116, v117
	v_max3_f32 v81, v81, v118, v119
	v_max3_f32 v81, v81, v120, v121
	v_max3_f32 v81, v81, v122, v123
	v_max3_f32 v81, v81, v124, v125
	s_waitcnt lgkmcnt(2)
	v_mfma_f32_32x32x16_bf16 v[0:15], v[86:89], v[90:93], v[0:15]
	ds_read_b64_tr_b16 v[86:87], v214 offset:49152
	ds_read_b64_tr_b16 v[88:89], v214 offset:51200
	ds_read_b64_tr_b16 v[90:91], v213 offset:53248
	ds_read_b64_tr_b16 v[92:93], v213 offset:55296
	v_max3_f32 v81, v81, v126, v127
	v_max3_f32 v81, v81, v216, v217
	v_max3_f32 v81, v81, v218, v219
	v_max3_f32 v81, v81, v220, v221
	v_max3_f32 v81, v81, v222, v223
	v_max3_f32 v81, v81, v224, v225
	s_waitcnt lgkmcnt(4)
	v_mfma_f32_32x32x16_bf16 v[48:63], v[94:97], v[82:85], v[48:63]
	ds_read_b64_tr_b16 v[94:95], v215 offset:49152
	ds_read_b64_tr_b16 v[96:97], v215 offset:51200
	ds_read_b64_tr_b16 v[98:99], v214 offset:53248
	ds_read_b64_tr_b16 v[100:101], v214 offset:55296
	v_max3_f32 v81, v81, v226, v227
	v_max3_f32 v81, v81, v228, v229
	v_max3_f32 v107, v81, v230, v231
	v_pk_add_f32 v[196:197], v[194:195], v[106:107]
	v_mov_b64_e32 v[144:145], v[216:217]
	s_waitcnt lgkmcnt(6)
	v_mfma_f32_32x32x16_bf16 v[32:47], v[86:89], v[82:85], v[32:47]
	ds_read_b64_tr_b16 v[86:87], v248 offset:49152
	ds_read_b64_tr_b16 v[88:89], v248 offset:51200
	ds_read_b64_tr_b16 v[102:103], v215 offset:53248
	ds_read_b64_tr_b16 v[104:105], v215 offset:55296
	s_waitcnt lgkmcnt(6)
	v_mfma_f32_32x32x16_bf16 v[16:31], v[94:97], v[82:85], v[16:31]
	ds_read_b64_tr_b16 v[94:95], v248 offset:53248
	ds_read_b64_tr_b16 v[96:97], v248 offset:55296
	s_waitcnt vmcnt(0)
	s_waitcnt lgkmcnt(4)
	v_mfma_f32_32x32x16_bf16 v[0:15], v[86:89], v[82:85], v[0:15]
	v_cvt_pk_bf16_f32 v85, v110, v111
	v_cvt_pk_bf16_f32 v84, v108, v109
	v_cvt_pk_bf16_f32 v83, v138, v139
	v_cvt_pk_bf16_f32 v82, v136, v137
	s_nop 1
	v_mfma_f32_32x32x16_bf16 v[48:63], v[90:93], v[82:85], v[48:63]
	s_waitcnt lgkmcnt(0)
	s_barrier
	v_mfma_f32_32x32x16_bf16 v[32:47], v[98:101], v[82:85], v[32:47]
	v_mfma_f32_32x32x16_bf16 v[16:31], v[102:105], v[82:85], v[16:31]
	v_mfma_f32_32x32x16_bf16 v[0:15], v[94:97], v[82:85], v[0:15]
	s_cbranch_vccnz .LBB0_432

.LBB0_432:
	ds_bpermute_b32 v64, v204, v196
	s_mov_b64 s[6:7], -1
	s_waitcnt lgkmcnt(0)
	v_add_f32_e32 v64, v196, v64
	v_div_scale_f32 v65, s[4:5], v64, v64, 1.0
	v_rcp_f32_e32 v66, v65
	v_div_scale_f32 v67, vcc, 1.0, v64, 1.0
	s_and_b64 s[4:5], exec, s[30:31]
	v_fma_f32 v68, -v65, v66, 1.0
	v_fmac_f32_e32 v66, v68, v66
	v_mul_f32_e32 v68, v67, v66
	v_fma_f32 v69, -v65, v68, v67
	v_fmac_f32_e32 v68, v69, v66
	v_fma_f32 v65, -v65, v68, v67
	v_div_fmas_f32 v65, v65, v66, v68
	v_div_fixup_f32 v64, v65, v64, 1.0
	s_mov_b64 vcc, s[4:5]
	s_cbranch_vccz .LBB0_434
	global_load_dwordx4 v[116:119], v[188:189], off
	global_load_dwordx4 v[120:123], v[188:189], off offset:32
	global_load_dwordx4 v[124:127], v[188:189], off offset:64
	global_load_dwordx4 v[128:131], v[188:189], off offset:96
	global_load_dwordx4 v[132:135], v[188:189], off offset:128
	global_load_dwordx4 v[136:139], v[188:189], off offset:160
	global_load_dwordx4 v[140:143], v[188:189], off offset:192
	global_load_dwordx4 v[144:147], v[188:189], off offset:224
	ds_read2st64_b32 v[68:69], v210 offset0:224 offset1:225
	v_mul_f32_e32 v66, v205, v64
	ds_read2st64_b32 v[70:71], v210 offset0:226 offset1:227
	ds_read2st64_b32 v[72:73], v210 offset0:228 offset1:229
	ds_read2st64_b32 v[74:75], v210 offset0:230 offset1:231
	v_mov_b32_e32 v88, v29
	s_waitcnt lgkmcnt(3)
	v_and_b32_e32 v67, 0xffff0000, v68
	v_lshlrev_b32_e32 v65, 16, v68
	v_fma_f32 v67, -v49, v66, v67
	v_fma_f32 v65, -v48, v66, v65
	v_mul_f32_e32 v67, v67, v67
	v_and_b32_e32 v68, 0xffff0000, v69
	v_fmac_f32_e32 v67, v65, v65
	v_lshlrev_b32_e32 v65, 16, v69
	v_fma_f32 v68, -v51, v66, v68
	v_fma_f32 v65, -v50, v66, v65
	v_mul_f32_e32 v68, v68, v68
	v_fmac_f32_e32 v68, v65, v65
	v_add_f32_e32 v65, v67, v68
	s_waitcnt lgkmcnt(2)
	v_and_b32_e32 v68, 0xffff0000, v70
	v_lshlrev_b32_e32 v67, 16, v70
	v_fma_f32 v68, -v53, v66, v68
	v_fma_f32 v67, -v52, v66, v67
	v_mul_f32_e32 v68, v68, v68
	v_fmac_f32_e32 v68, v67, v67
	v_add_f32_e32 v65, v65, v68
	v_and_b32_e32 v68, 0xffff0000, v71
	v_lshlrev_b32_e32 v67, 16, v71
	v_fma_f32 v68, -v55, v66, v68
	v_fma_f32 v67, -v54, v66, v67
	v_mul_f32_e32 v68, v68, v68
	v_fmac_f32_e32 v68, v67, v67
	v_add_f32_e32 v65, v65, v68
	s_waitcnt lgkmcnt(1)
	v_and_b32_e32 v68, 0xffff0000, v72
	v_lshlrev_b32_e32 v67, 16, v72
	v_fma_f32 v68, -v57, v66, v68
	v_fma_f32 v67, -v56, v66, v67
	v_mul_f32_e32 v68, v68, v68
	v_fmac_f32_e32 v68, v67, v67
	v_add_f32_e32 v65, v65, v68
	v_and_b32_e32 v68, 0xffff0000, v73
	v_lshlrev_b32_e32 v67, 16, v73
	v_fma_f32 v68, -v59, v66, v68
	v_fma_f32 v67, -v58, v66, v67
	v_mul_f32_e32 v68, v68, v68
	v_fmac_f32_e32 v68, v67, v67
	v_add_f32_e32 v65, v65, v68
	s_waitcnt lgkmcnt(0)
	v_and_b32_e32 v68, 0xffff0000, v74
	v_lshlrev_b32_e32 v67, 16, v74
	v_fma_f32 v68, -v61, v66, v68
	v_fma_f32 v67, -v60, v66, v67
	v_mul_f32_e32 v68, v68, v68
	v_fmac_f32_e32 v68, v67, v67
	v_add_f32_e32 v65, v65, v68
	v_and_b32_e32 v68, 0xffff0000, v75
	v_fma_f32 v68, -v63, v66, v68
	v_mul_f32_e32 v70, v68, v68
	ds_read2st64_b32 v[68:69], v210 offset0:232 offset1:233
	v_lshlrev_b32_e32 v67, 16, v75
	v_fma_f32 v67, -v62, v66, v67
	v_fmac_f32_e32 v70, v67, v67
	v_add_f32_e32 v65, v65, v70
	s_waitcnt lgkmcnt(0)
	v_lshlrev_b32_e32 v67, 16, v68
	v_and_b32_e32 v68, 0xffff0000, v68
	v_fma_f32 v68, -v33, v66, v68
	v_fma_f32 v67, -v32, v66, v67
	v_mul_f32_e32 v68, v68, v68
	v_fmac_f32_e32 v68, v67, v67
	v_add_f32_e32 v65, v65, v68
	v_and_b32_e32 v68, 0xffff0000, v69
	ds_read2st64_b32 v[70:71], v210 offset0:234 offset1:235
	ds_read2st64_b32 v[72:73], v210 offset0:236 offset1:237
	ds_read2st64_b32 v[74:75], v210 offset0:238 offset1:239
	v_lshlrev_b32_e32 v67, 16, v69
	v_fma_f32 v68, -v35, v66, v68
	v_fma_f32 v67, -v34, v66, v67
	v_mul_f32_e32 v68, v68, v68
	v_fmac_f32_e32 v68, v67, v67
	v_add_f32_e32 v65, v65, v68
	s_waitcnt lgkmcnt(2)
	v_and_b32_e32 v68, 0xffff0000, v70
	v_lshlrev_b32_e32 v67, 16, v70
	v_fma_f32 v68, -v37, v66, v68
	v_fma_f32 v67, -v36, v66, v67
	v_mul_f32_e32 v68, v68, v68
	v_fmac_f32_e32 v68, v67, v67
	v_add_f32_e32 v65, v65, v68
	v_and_b32_e32 v68, 0xffff0000, v71
	v_lshlrev_b32_e32 v67, 16, v71
	v_fma_f32 v68, -v39, v66, v68
	v_fma_f32 v67, -v38, v66, v67
	v_mul_f32_e32 v68, v68, v68
	v_fmac_f32_e32 v68, v67, v67
	v_add_f32_e32 v65, v65, v68
	s_waitcnt lgkmcnt(1)
	v_and_b32_e32 v68, 0xffff0000, v72
	v_lshlrev_b32_e32 v67, 16, v72
	v_fma_f32 v68, -v41, v66, v68
	v_fma_f32 v67, -v40, v66, v67
	v_mul_f32_e32 v68, v68, v68
	v_fmac_f32_e32 v68, v67, v67
	v_add_f32_e32 v65, v65, v68
	v_and_b32_e32 v68, 0xffff0000, v73
	v_lshlrev_b32_e32 v67, 16, v73
	v_fma_f32 v68, -v43, v66, v68
	v_fma_f32 v67, -v42, v66, v67
	v_mul_f32_e32 v68, v68, v68
	v_fmac_f32_e32 v68, v67, v67
	v_add_f32_e32 v65, v65, v68
	s_waitcnt lgkmcnt(0)
	v_and_b32_e32 v68, 0xffff0000, v74
	v_lshlrev_b32_e32 v67, 16, v74
	v_fma_f32 v68, -v45, v66, v68
	v_fma_f32 v67, -v44, v66, v67
	v_mul_f32_e32 v68, v68, v68
	v_fmac_f32_e32 v68, v67, v67
	v_add_f32_e32 v65, v65, v68
	v_and_b32_e32 v68, 0xffff0000, v75
	v_fma_f32 v68, -v47, v66, v68
	v_mul_f32_e32 v70, v68, v68
	ds_read2st64_b32 v[68:69], v210 offset0:240 offset1:241
	v_lshlrev_b32_e32 v67, 16, v75
	v_fma_f32 v67, -v46, v66, v67
	v_fmac_f32_e32 v70, v67, v67
	v_add_f32_e32 v65, v65, v70
	s_waitcnt lgkmcnt(0)
	v_lshlrev_b32_e32 v67, 16, v68
	v_and_b32_e32 v68, 0xffff0000, v68
	v_fma_f32 v68, -v17, v66, v68
	v_fma_f32 v67, -v16, v66, v67
	v_mul_f32_e32 v68, v68, v68
	v_fmac_f32_e32 v68, v67, v67
	v_add_f32_e32 v65, v65, v68
	v_and_b32_e32 v68, 0xffff0000, v69
	ds_read2st64_b32 v[70:71], v210 offset0:242 offset1:243
	ds_read2st64_b32 v[72:73], v210 offset0:244 offset1:245
	ds_read2st64_b32 v[74:75], v210 offset0:246 offset1:247
	v_lshlrev_b32_e32 v67, 16, v69
	v_fma_f32 v68, -v19, v66, v68
	v_fma_f32 v67, -v18, v66, v67
	v_mul_f32_e32 v68, v68, v68
	v_fmac_f32_e32 v68, v67, v67
	v_add_f32_e32 v65, v65, v68
	s_waitcnt lgkmcnt(2)
	v_and_b32_e32 v68, 0xffff0000, v70
	v_lshlrev_b32_e32 v67, 16, v70
	v_fma_f32 v68, -v21, v66, v68
	v_fma_f32 v67, -v20, v66, v67
	v_mul_f32_e32 v68, v68, v68
	v_fmac_f32_e32 v68, v67, v67
	v_add_f32_e32 v65, v65, v68
	v_and_b32_e32 v68, 0xffff0000, v71
	v_lshlrev_b32_e32 v67, 16, v71
	v_fma_f32 v68, -v23, v66, v68
	v_fma_f32 v67, -v22, v66, v67
	v_mul_f32_e32 v68, v68, v68
	v_fmac_f32_e32 v68, v67, v67
	v_add_f32_e32 v65, v65, v68
	s_waitcnt lgkmcnt(1)
	v_and_b32_e32 v68, 0xffff0000, v72
	v_lshlrev_b32_e32 v67, 16, v72
	v_fma_f32 v68, -v25, v66, v68
	v_fma_f32 v67, -v24, v66, v67
	v_mul_f32_e32 v68, v68, v68
	v_fmac_f32_e32 v68, v67, v67
	v_add_f32_e32 v65, v65, v68
	v_and_b32_e32 v68, 0xffff0000, v73
	v_lshlrev_b32_e32 v67, 16, v73
	v_fma_f32 v68, -v27, v66, v68
	v_fma_f32 v67, -v26, v66, v67
	v_mul_f32_e32 v68, v68, v68
	v_fmac_f32_e32 v68, v67, v67
	s_waitcnt lgkmcnt(0)
	v_and_b32_e32 v71, 0xffff0000, v75
	v_and_b32_e32 v70, 0xffff0000, v74
	v_mov_b32_e32 v89, v31
	v_add_f32_e32 v65, v65, v68
	v_lshlrev_b32_e32 v69, 16, v75
	v_lshlrev_b32_e32 v68, 16, v74
	v_mov_b32_e32 v86, v28
	v_mov_b32_e32 v87, v30
	v_pk_fma_f32 v[70:71], v[88:89], v[66:67], v[70:71] op_sel_hi:[1,0,1] neg_lo:[1,0,0] neg_hi:[1,0,0]
	v_pk_fma_f32 v[68:69], v[86:87], v[66:67], v[68:69] op_sel_hi:[1,0,1] neg_lo:[1,0,0] neg_hi:[1,0,0]
	v_pk_mul_f32 v[70:71], v[70:71], v[70:71]
	v_mov_b32_e32 v80, v1
	v_pk_fma_f32 v[68:69], v[68:69], v[68:69], v[70:71]
	ds_read2st64_b32 v[70:71], v210 offset0:248 offset1:249
	v_add_f32_e32 v65, v65, v68
	v_add_f32_e32 v65, v65, v69
	ds_read2st64_b32 v[68:69], v210 offset0:250 offset1:251
	ds_read2st64_b32 v[72:73], v210 offset0:252 offset1:253
	ds_read2st64_b32 v[76:77], v210 offset0:254 offset1:255
	s_waitcnt vmcnt(0)
	s_nop 1
	v_mov_b32_e32 v90, v116
	v_mov_b32_e32 v91, v117
	v_mov_b32_e32 v92, v118
	v_mov_b32_e32 v93, v119
	s_load_dwordx2 s[4:5], s[0:1], 0x68
	s_waitcnt lgkmcnt(0)
	v_lshlrev_b32_e32 v75, 16, v71
	v_lshlrev_b32_e32 v74, 16, v70
	v_and_b32_e32 v71, 0xffff0000, v71
	v_and_b32_e32 v70, 0xffff0000, v70
	v_mov_b32_e32 v81, v3
	v_mov_b32_e32 v78, v0
	v_mov_b32_e32 v79, v2
	v_pk_fma_f32 v[70:71], v[80:81], v[66:67], v[70:71] op_sel_hi:[1,0,1] neg_lo:[1,0,0] neg_hi:[1,0,0]
	v_pk_fma_f32 v[74:75], v[78:79], v[66:67], v[74:75] op_sel_hi:[1,0,1] neg_lo:[1,0,0] neg_hi:[1,0,0]
	v_pk_mul_f32 v[70:71], v[70:71], v[70:71]
	ds_read_b128 v[94:97], v251
	v_pk_fma_f32 v[70:71], v[74:75], v[74:75], v[70:71]
	v_mov_b32_e32 v84, v5
	v_add_f32_e32 v65, v65, v70
	v_add_f32_e32 v65, v65, v71
	v_lshlrev_b32_e32 v71, 16, v69
	v_lshlrev_b32_e32 v70, 16, v68
	v_and_b32_e32 v69, 0xffff0000, v69
	v_and_b32_e32 v68, 0xffff0000, v68
	v_mov_b32_e32 v85, v7
	v_mov_b32_e32 v82, v4
	v_mov_b32_e32 v83, v6
	v_pk_fma_f32 v[68:69], v[84:85], v[66:67], v[68:69] op_sel_hi:[1,0,1] neg_lo:[1,0,0] neg_hi:[1,0,0]
	v_pk_fma_f32 v[70:71], v[82:83], v[66:67], v[70:71] op_sel_hi:[1,0,1] neg_lo:[1,0,0] neg_hi:[1,0,0]
	v_pk_mul_f32 v[68:69], v[68:69], v[68:69]
	v_and_b32_e32 v75, 0xffff0000, v73
	v_pk_fma_f32 v[68:69], v[70:71], v[70:71], v[68:69]
	v_and_b32_e32 v74, 0xffff0000, v72
	v_add_f32_e32 v65, v65, v68
	v_add_f32_e32 v65, v65, v69
	v_lshlrev_b32_e32 v69, 16, v73
	v_lshlrev_b32_e32 v68, 16, v72
	v_mov_b32_e32 v72, v9
	v_mov_b32_e32 v73, v11
	v_mov_b32_e32 v70, v8
	v_mov_b32_e32 v71, v10
	v_pk_fma_f32 v[74:75], v[72:73], v[66:67], v[74:75] op_sel_hi:[1,0,1] neg_lo:[1,0,0] neg_hi:[1,0,0]
	v_pk_fma_f32 v[68:69], v[70:71], v[66:67], v[68:69] op_sel_hi:[1,0,1] neg_lo:[1,0,0] neg_hi:[1,0,0]
	v_pk_mul_f32 v[74:75], v[74:75], v[74:75]
	v_and_b32_e32 v99, 0xffff0000, v77
	v_pk_fma_f32 v[68:69], v[68:69], v[68:69], v[74:75]
	v_and_b32_e32 v98, 0xffff0000, v76
	v_add_f32_e32 v65, v65, v68
	v_add_f32_e32 v65, v65, v69
	v_lshlrev_b32_e32 v69, 16, v77
	v_lshlrev_b32_e32 v68, 16, v76
	v_mov_b32_e32 v76, v13
	v_mov_b32_e32 v77, v15
	v_mov_b32_e32 v74, v12
	v_mov_b32_e32 v75, v14
	v_pk_fma_f32 v[98:99], v[76:77], v[66:67], v[98:99] op_sel_hi:[1,0,1] neg_lo:[1,0,0] neg_hi:[1,0,0]
	v_pk_fma_f32 v[68:69], v[74:75], v[66:67], v[68:69] op_sel_hi:[1,0,1] neg_lo:[1,0,0] neg_hi:[1,0,0]
	v_pk_mul_f32 v[98:99], v[98:99], v[98:99]
	ds_read2st64_b32 v[102:103], v210 offset0:224 offset1:225
	ds_read2st64_b32 v[104:105], v210 offset0:226 offset1:227
	v_pk_fma_f32 v[68:69], v[68:69], v[68:69], v[98:99]
	ds_read_b128 v[98:101], v251 offset:16
	v_add_f32_e32 v65, v65, v68
	v_add_f32_e32 v65, v65, v69
	ds_bpermute_b32 v67, v204, v65
	s_waitcnt lgkmcnt(0)
	v_add_f32_e32 v65, v65, v67
	v_fmamk_f32 v65, v65, 0x3c000000, v211
	v_mul_f32_e32 v67, 0x4b800000, v65
	v_cmp_gt_f32_e32 vcc, s72, v65
	s_nop 0
	v_lshlrev_b32_e32 v110, 16, v90
	v_cndmask_b32_e32 v65, v65, v67, vcc
	v_rsq_f32_e32 v65, v65
	v_and_b32_e32 v111, 0xffff0000, v90
	v_mul_f32_e32 v67, 0x45800000, v65
	v_cndmask_b32_e32 v65, v65, v67, vcc
	v_mul_f32_e32 v68, 0x3f4ccccd, v65
	v_lshlrev_b32_e32 v65, 16, v102
	v_fma_f32 v106, -v48, v66, v65
	v_and_b32_e32 v65, 0xffff0000, v102
	v_fma_f32 v107, -v49, v66, v65
	v_lshlrev_b32_e32 v65, 16, v104
	v_fma_f32 v108, -v52, v66, v65
	v_and_b32_e32 v65, 0xffff0000, v104
	v_fma_f32 v109, -v53, v66, v65
	v_lshlrev_b32_e32 v65, 16, v103
	v_fma_f32 v102, -v50, v66, v65
	v_and_b32_e32 v65, 0xffff0000, v103
	v_fma_f32 v103, -v51, v66, v65
	v_lshlrev_b32_e32 v65, 16, v105
	v_fma_f32 v104, -v54, v66, v65
	v_and_b32_e32 v65, 0xffff0000, v105
	v_fma_f32 v105, -v55, v66, v65
	v_mul_f32_e32 v65, 0xbfb8aa3b, v110
	v_exp_f32_e32 v65, v65
	v_mul_f32_e32 v67, 0xbfb8aa3b, v111
	v_exp_f32_e32 v67, v67
	v_permlane32_swap_b32_e32 v106, v108
	v_add_f32_e32 v65, 1.0, v65
	v_rcp_f32_e32 v112, v65
	v_add_f32_e32 v65, 1.0, v67
	v_rcp_f32_e32 v113, v65
	v_permlane32_swap_b32_e32 v107, v109
	v_pk_mul_f32 v[106:107], v[68:69], v[106:107] op_sel_hi:[0,1]
	s_nop 0
	v_pk_mul_f32 v[94:95], v[94:95], v[106:107]
	v_pk_mul_f32 v[106:107], v[112:113], v[110:111]
	v_lshlrev_b32_e32 v110, 16, v91
	v_and_b32_e32 v111, 0xffff0000, v91
	v_mul_f32_e32 v65, 0xbfb8aa3b, v110
	v_exp_f32_e32 v65, v65
	v_mul_f32_e32 v67, 0xbfb8aa3b, v111
	v_exp_f32_e32 v67, v67
	v_permlane32_swap_b32_e32 v102, v104
	v_permlane32_swap_b32_e32 v103, v105
	v_add_f32_e32 v65, 1.0, v65
	v_pk_mul_f32 v[90:91], v[94:95], v[106:107]
	v_rcp_f32_e32 v94, v65
	v_add_f32_e32 v65, 1.0, v67
	v_pk_mul_f32 v[102:103], v[68:69], v[102:103] op_sel_hi:[0,1]
	v_rcp_f32_e32 v95, v65
	v_pk_mul_f32 v[96:97], v[96:97], v[102:103]
	v_lshlrev_b32_e32 v102, 16, v92
	v_and_b32_e32 v103, 0xffff0000, v92
	v_mul_f32_e32 v65, 0xbfb8aa3b, v102
	v_exp_f32_e32 v65, v65
	v_mul_f32_e32 v67, 0xbfb8aa3b, v103
	v_exp_f32_e32 v67, v67
	v_pk_mul_f32 v[94:95], v[94:95], v[110:111]
	v_cvt_pk_bf16_f32 v90, v90, v91
	v_pk_mul_f32 v[94:95], v[96:97], v[94:95]
	v_add_f32_e32 v65, 1.0, v65
	v_cvt_pk_bf16_f32 v91, v94, v95
	v_pk_mul_f32 v[94:95], v[68:69], v[108:109] op_sel_hi:[0,1]
	v_rcp_f32_e32 v96, v65
	v_add_f32_e32 v65, 1.0, v67
	s_nop 0
	v_pk_mul_f32 v[94:95], v[98:99], v[94:95]
	v_lshlrev_b32_e32 v98, 16, v93
	v_rcp_f32_e32 v97, v65
	v_and_b32_e32 v99, 0xffff0000, v93
	v_mul_f32_e32 v65, 0xbfb8aa3b, v98
	v_exp_f32_e32 v65, v65
	v_mul_f32_e32 v67, 0xbfb8aa3b, v99
	v_exp_f32_e32 v67, v67
	v_pk_mul_f32 v[96:97], v[96:97], v[102:103]
	v_add_f32_e32 v65, 1.0, v65
	v_pk_mul_f32 v[92:93], v[94:95], v[96:97]
	v_rcp_f32_e32 v94, v65
	v_add_f32_e32 v65, 1.0, v67
	v_rcp_f32_e32 v95, v65
	v_pk_mul_f32 v[96:97], v[68:69], v[104:105] op_sel_hi:[0,1]
	v_pk_mul_f32 v[96:97], v[100:101], v[96:97]
	v_cvt_pk_bf16_f32 v92, v92, v93
	v_pk_mul_f32 v[94:95], v[94:95], v[98:99]
	s_nop 0
	v_pk_mul_f32 v[94:95], v[96:97], v[94:95]
	s_nop 0
	v_cvt_pk_bf16_f32 v93, v94, v95
	global_store_dwordx4 v[186:187], v[90:93], off
	s_nop 1
	v_mov_b32_e32 v90, v120
	v_mov_b32_e32 v91, v121
	v_mov_b32_e32 v92, v122
	v_mov_b32_e32 v93, v123
	ds_read_b128 v[94:97], v251 offset:64
	ds_read_b128 v[98:101], v251 offset:80
	ds_read2st64_b32 v[102:103], v210 offset0:228 offset1:229
	ds_read2st64_b32 v[104:105], v210 offset0:230 offset1:231
	s_waitcnt lgkmcnt(1)
	v_lshlrev_b32_e32 v65, 16, v102
	v_fma_f32 v106, -v56, v66, v65
	v_and_b32_e32 v65, 0xffff0000, v102
	v_fma_f32 v107, -v57, v66, v65
	s_waitcnt lgkmcnt(0)
	v_lshlrev_b32_e32 v65, 16, v104
	v_fma_f32 v108, -v60, v66, v65
	v_and_b32_e32 v65, 0xffff0000, v104
	v_fma_f32 v109, -v61, v66, v65
	v_lshlrev_b32_e32 v65, 16, v103
	v_fma_f32 v102, -v58, v66, v65
	v_and_b32_e32 v65, 0xffff0000, v103
	v_fma_f32 v103, -v59, v66, v65
	v_lshlrev_b32_e32 v65, 16, v105
	v_fma_f32 v104, -v62, v66, v65
	v_and_b32_e32 v65, 0xffff0000, v105
	v_fma_f32 v105, -v63, v66, v65
	v_permlane32_swap_b32_e32 v106, v108
	v_permlane32_swap_b32_e32 v107, v109
	v_pk_mul_f32 v[106:107], v[68:69], v[106:107] op_sel_hi:[0,1]
	v_permlane32_swap_b32_e32 v102, v104
	v_permlane32_swap_b32_e32 v103, v105
	v_pk_mul_f32 v[102:103], v[68:69], v[102:103] op_sel_hi:[0,1]
	s_nop 0
	v_lshlrev_b32_e32 v110, 16, v90
	v_and_b32_e32 v111, 0xffff0000, v90
	v_mul_f32_e32 v65, 0xbfb8aa3b, v110
	v_exp_f32_e32 v65, v65
	v_mul_f32_e32 v67, 0xbfb8aa3b, v111
	v_exp_f32_e32 v67, v67
	s_nop 0
	v_pk_mul_f32 v[94:95], v[106:107], v[94:95]
	v_add_f32_e32 v65, 1.0, v65
	v_rcp_f32_e32 v112, v65
	v_add_f32_e32 v65, 1.0, v67
	v_rcp_f32_e32 v113, v65
	v_pk_mul_f32 v[96:97], v[96:97], v[102:103]
	v_lshlrev_b32_e32 v102, 16, v92
	v_and_b32_e32 v103, 0xffff0000, v92
	v_pk_mul_f32 v[106:107], v[112:113], v[110:111]
	v_lshlrev_b32_e32 v110, 16, v91
	v_and_b32_e32 v111, 0xffff0000, v91
	v_mul_f32_e32 v65, 0xbfb8aa3b, v110
	v_exp_f32_e32 v65, v65
	v_mul_f32_e32 v67, 0xbfb8aa3b, v111
	v_exp_f32_e32 v67, v67
	v_pk_mul_f32 v[90:91], v[94:95], v[106:107]
	v_add_f32_e32 v65, 1.0, v65
	v_rcp_f32_e32 v94, v65
	v_add_f32_e32 v65, 1.0, v67
	v_rcp_f32_e32 v95, v65
	v_mul_f32_e32 v65, 0xbfb8aa3b, v102
	v_exp_f32_e32 v65, v65
	v_mul_f32_e32 v67, 0xbfb8aa3b, v103
	v_exp_f32_e32 v67, v67
	v_pk_mul_f32 v[94:95], v[94:95], v[110:111]
	v_cvt_pk_bf16_f32 v90, v90, v91
	v_pk_mul_f32 v[94:95], v[96:97], v[94:95]
	v_add_f32_e32 v65, 1.0, v65
	v_cvt_pk_bf16_f32 v91, v94, v95
	v_pk_mul_f32 v[94:95], v[68:69], v[108:109] op_sel_hi:[0,1]
	v_rcp_f32_e32 v96, v65
	v_add_f32_e32 v65, 1.0, v67
	s_nop 0
	v_pk_mul_f32 v[94:95], v[94:95], v[98:99]
	v_lshlrev_b32_e32 v98, 16, v93
	v_rcp_f32_e32 v97, v65
	v_and_b32_e32 v99, 0xffff0000, v93
	v_mul_f32_e32 v65, 0xbfb8aa3b, v98
	v_exp_f32_e32 v65, v65
	v_mul_f32_e32 v67, 0xbfb8aa3b, v99
	v_exp_f32_e32 v67, v67
	v_pk_mul_f32 v[96:97], v[96:97], v[102:103]
	v_add_f32_e32 v65, 1.0, v65
	v_pk_mul_f32 v[92:93], v[94:95], v[96:97]
	v_rcp_f32_e32 v94, v65
	v_add_f32_e32 v65, 1.0, v67
	v_rcp_f32_e32 v95, v65
	v_pk_mul_f32 v[96:97], v[68:69], v[104:105] op_sel_hi:[0,1]
	v_pk_mul_f32 v[96:97], v[96:97], v[100:101]
	v_cvt_pk_bf16_f32 v92, v92, v93
	v_pk_mul_f32 v[94:95], v[94:95], v[98:99]
	s_nop 0
	v_pk_mul_f32 v[94:95], v[96:97], v[94:95]
	s_nop 0
	v_cvt_pk_bf16_f32 v93, v94, v95
	global_store_dwordx4 v[186:187], v[90:93], off offset:32
	s_nop 1
	v_mov_b32_e32 v90, v124
	v_mov_b32_e32 v91, v125
	v_mov_b32_e32 v92, v126
	v_mov_b32_e32 v93, v127
	ds_read_b128 v[94:97], v251 offset:128
	ds_read_b128 v[98:101], v251 offset:144
	ds_read2st64_b32 v[102:103], v210 offset0:232 offset1:233
	ds_read2st64_b32 v[104:105], v210 offset0:234 offset1:235
	s_waitcnt lgkmcnt(1)
	v_lshlrev_b32_e32 v65, 16, v102
	v_fma_f32 v106, -v32, v66, v65
	v_and_b32_e32 v65, 0xffff0000, v102
	v_fma_f32 v107, -v33, v66, v65
	s_waitcnt lgkmcnt(0)
	v_lshlrev_b32_e32 v65, 16, v104
	v_fma_f32 v108, -v36, v66, v65
	v_and_b32_e32 v65, 0xffff0000, v104
	v_fma_f32 v109, -v37, v66, v65
	v_lshlrev_b32_e32 v65, 16, v103
	v_fma_f32 v102, -v34, v66, v65
	v_and_b32_e32 v65, 0xffff0000, v103
	v_fma_f32 v103, -v35, v66, v65
	v_lshlrev_b32_e32 v65, 16, v105
	v_fma_f32 v104, -v38, v66, v65
	v_and_b32_e32 v65, 0xffff0000, v105
	v_fma_f32 v105, -v39, v66, v65
	v_permlane32_swap_b32_e32 v106, v108
	v_permlane32_swap_b32_e32 v107, v109
	v_pk_mul_f32 v[106:107], v[68:69], v[106:107] op_sel_hi:[0,1]
	v_permlane32_swap_b32_e32 v102, v104
	v_permlane32_swap_b32_e32 v103, v105
	v_pk_mul_f32 v[102:103], v[68:69], v[102:103] op_sel_hi:[0,1]
	s_nop 0
	v_lshlrev_b32_e32 v110, 16, v90
	v_and_b32_e32 v111, 0xffff0000, v90
	v_mul_f32_e32 v65, 0xbfb8aa3b, v110
	v_exp_f32_e32 v65, v65
	v_mul_f32_e32 v67, 0xbfb8aa3b, v111
	v_exp_f32_e32 v67, v67
	s_nop 0
	v_pk_mul_f32 v[94:95], v[106:107], v[94:95]
	v_add_f32_e32 v65, 1.0, v65
	v_rcp_f32_e32 v112, v65
	v_add_f32_e32 v65, 1.0, v67
	v_rcp_f32_e32 v113, v65
	v_pk_mul_f32 v[96:97], v[96:97], v[102:103]
	v_lshlrev_b32_e32 v102, 16, v92
	v_and_b32_e32 v103, 0xffff0000, v92
	v_pk_mul_f32 v[106:107], v[112:113], v[110:111]
	v_lshlrev_b32_e32 v110, 16, v91
	v_and_b32_e32 v111, 0xffff0000, v91
	v_mul_f32_e32 v65, 0xbfb8aa3b, v110
	v_exp_f32_e32 v65, v65
	v_mul_f32_e32 v67, 0xbfb8aa3b, v111
	v_exp_f32_e32 v67, v67
	v_pk_mul_f32 v[90:91], v[94:95], v[106:107]
	v_add_f32_e32 v65, 1.0, v65
	v_rcp_f32_e32 v94, v65
	v_add_f32_e32 v65, 1.0, v67
	v_rcp_f32_e32 v95, v65
	v_mul_f32_e32 v65, 0xbfb8aa3b, v102
	v_exp_f32_e32 v65, v65
	v_mul_f32_e32 v67, 0xbfb8aa3b, v103
	v_exp_f32_e32 v67, v67
	v_pk_mul_f32 v[94:95], v[94:95], v[110:111]
	v_cvt_pk_bf16_f32 v90, v90, v91
	v_pk_mul_f32 v[94:95], v[96:97], v[94:95]
	v_add_f32_e32 v65, 1.0, v65
	v_cvt_pk_bf16_f32 v91, v94, v95
	v_pk_mul_f32 v[94:95], v[68:69], v[108:109] op_sel_hi:[0,1]
	v_rcp_f32_e32 v96, v65
	v_add_f32_e32 v65, 1.0, v67
	s_nop 0
	v_pk_mul_f32 v[94:95], v[94:95], v[98:99]
	v_lshlrev_b32_e32 v98, 16, v93
	v_rcp_f32_e32 v97, v65
	v_and_b32_e32 v99, 0xffff0000, v93
	v_mul_f32_e32 v65, 0xbfb8aa3b, v98
	v_exp_f32_e32 v65, v65
	v_mul_f32_e32 v67, 0xbfb8aa3b, v99
	v_exp_f32_e32 v67, v67
	v_pk_mul_f32 v[96:97], v[96:97], v[102:103]
	v_add_f32_e32 v65, 1.0, v65
	v_pk_mul_f32 v[92:93], v[94:95], v[96:97]
	v_rcp_f32_e32 v94, v65
	v_add_f32_e32 v65, 1.0, v67
	v_rcp_f32_e32 v95, v65
	v_pk_mul_f32 v[96:97], v[68:69], v[104:105] op_sel_hi:[0,1]
	v_pk_mul_f32 v[96:97], v[96:97], v[100:101]
	v_cvt_pk_bf16_f32 v92, v92, v93
	v_pk_mul_f32 v[94:95], v[94:95], v[98:99]
	s_nop 0
	v_pk_mul_f32 v[94:95], v[96:97], v[94:95]
	s_nop 0
	v_cvt_pk_bf16_f32 v93, v94, v95
	global_store_dwordx4 v[186:187], v[90:93], off offset:64
	s_nop 1
	v_mov_b32_e32 v90, v128
	v_mov_b32_e32 v91, v129
	v_mov_b32_e32 v92, v130
	v_mov_b32_e32 v93, v131
	ds_read_b128 v[94:97], v251 offset:192
	ds_read_b128 v[98:101], v251 offset:208
	ds_read2st64_b32 v[102:103], v210 offset0:236 offset1:237
	ds_read2st64_b32 v[104:105], v210 offset0:238 offset1:239
	s_waitcnt lgkmcnt(1)
	v_lshlrev_b32_e32 v65, 16, v102
	v_fma_f32 v106, -v40, v66, v65
	v_and_b32_e32 v65, 0xffff0000, v102
	v_fma_f32 v107, -v41, v66, v65
	s_waitcnt lgkmcnt(0)
	v_lshlrev_b32_e32 v65, 16, v104
	v_fma_f32 v108, -v44, v66, v65
	v_and_b32_e32 v65, 0xffff0000, v104
	v_fma_f32 v109, -v45, v66, v65
	v_lshlrev_b32_e32 v65, 16, v103
	v_fma_f32 v102, -v42, v66, v65
	v_and_b32_e32 v65, 0xffff0000, v103
	v_fma_f32 v103, -v43, v66, v65
	v_lshlrev_b32_e32 v65, 16, v105
	v_fma_f32 v104, -v46, v66, v65
	v_and_b32_e32 v65, 0xffff0000, v105
	v_fma_f32 v105, -v47, v66, v65
	v_permlane32_swap_b32_e32 v106, v108
	v_permlane32_swap_b32_e32 v107, v109
	v_pk_mul_f32 v[106:107], v[68:69], v[106:107] op_sel_hi:[0,1]
	v_permlane32_swap_b32_e32 v102, v104
	v_permlane32_swap_b32_e32 v103, v105
	v_pk_mul_f32 v[102:103], v[68:69], v[102:103] op_sel_hi:[0,1]
	s_nop 0
	v_lshlrev_b32_e32 v110, 16, v90
	v_and_b32_e32 v111, 0xffff0000, v90
	v_mul_f32_e32 v65, 0xbfb8aa3b, v110
	v_exp_f32_e32 v65, v65
	v_mul_f32_e32 v67, 0xbfb8aa3b, v111
	v_exp_f32_e32 v67, v67
	s_nop 0
	v_pk_mul_f32 v[94:95], v[106:107], v[94:95]
	v_add_f32_e32 v65, 1.0, v65
	v_rcp_f32_e32 v112, v65
	v_add_f32_e32 v65, 1.0, v67
	v_rcp_f32_e32 v113, v65
	v_pk_mul_f32 v[96:97], v[96:97], v[102:103]
	v_lshlrev_b32_e32 v102, 16, v92
	v_and_b32_e32 v103, 0xffff0000, v92
	v_pk_mul_f32 v[106:107], v[112:113], v[110:111]
	v_lshlrev_b32_e32 v110, 16, v91
	v_and_b32_e32 v111, 0xffff0000, v91
	v_mul_f32_e32 v65, 0xbfb8aa3b, v110
	v_exp_f32_e32 v65, v65
	v_mul_f32_e32 v67, 0xbfb8aa3b, v111
	v_exp_f32_e32 v67, v67
	v_pk_mul_f32 v[90:91], v[94:95], v[106:107]
	v_add_f32_e32 v65, 1.0, v65
	v_rcp_f32_e32 v94, v65
	v_add_f32_e32 v65, 1.0, v67
	v_rcp_f32_e32 v95, v65
	v_mul_f32_e32 v65, 0xbfb8aa3b, v102
	v_exp_f32_e32 v65, v65
	v_mul_f32_e32 v67, 0xbfb8aa3b, v103
	v_exp_f32_e32 v67, v67
	v_pk_mul_f32 v[94:95], v[94:95], v[110:111]
	v_cvt_pk_bf16_f32 v90, v90, v91
	v_pk_mul_f32 v[94:95], v[96:97], v[94:95]
	v_add_f32_e32 v65, 1.0, v65
	v_cvt_pk_bf16_f32 v91, v94, v95
	v_pk_mul_f32 v[94:95], v[68:69], v[108:109] op_sel_hi:[0,1]
	v_rcp_f32_e32 v96, v65
	v_add_f32_e32 v65, 1.0, v67
	s_nop 0
	v_pk_mul_f32 v[94:95], v[94:95], v[98:99]
	v_lshlrev_b32_e32 v98, 16, v93
	v_rcp_f32_e32 v97, v65
	v_and_b32_e32 v99, 0xffff0000, v93
	v_mul_f32_e32 v65, 0xbfb8aa3b, v98
	v_exp_f32_e32 v65, v65
	v_mul_f32_e32 v67, 0xbfb8aa3b, v99
	v_exp_f32_e32 v67, v67
	v_pk_mul_f32 v[96:97], v[96:97], v[102:103]
	v_add_f32_e32 v65, 1.0, v65
	v_pk_mul_f32 v[92:93], v[94:95], v[96:97]
	v_rcp_f32_e32 v94, v65
	v_add_f32_e32 v65, 1.0, v67
	v_rcp_f32_e32 v95, v65
	v_pk_mul_f32 v[96:97], v[68:69], v[104:105] op_sel_hi:[0,1]
	v_pk_mul_f32 v[96:97], v[96:97], v[100:101]
	v_cvt_pk_bf16_f32 v92, v92, v93
	v_pk_mul_f32 v[94:95], v[94:95], v[98:99]
	s_nop 0
	v_pk_mul_f32 v[94:95], v[96:97], v[94:95]
	s_nop 0
	v_cvt_pk_bf16_f32 v93, v94, v95
	global_store_dwordx4 v[186:187], v[90:93], off offset:96
	s_nop 1
	v_mov_b32_e32 v90, v132
	v_mov_b32_e32 v91, v133
	v_mov_b32_e32 v92, v134
	v_mov_b32_e32 v93, v135
	ds_read_b128 v[94:97], v251 offset:256
	ds_read_b128 v[98:101], v251 offset:272
	ds_read2st64_b32 v[102:103], v210 offset0:240 offset1:241
	ds_read2st64_b32 v[104:105], v210 offset0:242 offset1:243
	s_waitcnt lgkmcnt(1)
	v_lshlrev_b32_e32 v65, 16, v102
	v_fma_f32 v106, -v16, v66, v65
	v_and_b32_e32 v65, 0xffff0000, v102
	v_fma_f32 v107, -v17, v66, v65
	s_waitcnt lgkmcnt(0)
	v_lshlrev_b32_e32 v65, 16, v104
	v_fma_f32 v108, -v20, v66, v65
	v_and_b32_e32 v65, 0xffff0000, v104
	v_fma_f32 v109, -v21, v66, v65
	v_lshlrev_b32_e32 v65, 16, v103
	v_fma_f32 v102, -v18, v66, v65
	v_and_b32_e32 v65, 0xffff0000, v103
	v_fma_f32 v103, -v19, v66, v65
	v_lshlrev_b32_e32 v65, 16, v105
	v_fma_f32 v104, -v22, v66, v65
	v_and_b32_e32 v65, 0xffff0000, v105
	v_fma_f32 v105, -v23, v66, v65
	v_permlane32_swap_b32_e32 v106, v108
	v_permlane32_swap_b32_e32 v107, v109
	v_pk_mul_f32 v[106:107], v[68:69], v[106:107] op_sel_hi:[0,1]
	v_permlane32_swap_b32_e32 v102, v104
	v_permlane32_swap_b32_e32 v103, v105
	v_pk_mul_f32 v[102:103], v[68:69], v[102:103] op_sel_hi:[0,1]
	s_nop 0
	v_lshlrev_b32_e32 v110, 16, v90
	v_and_b32_e32 v111, 0xffff0000, v90
	v_mul_f32_e32 v65, 0xbfb8aa3b, v110
	v_exp_f32_e32 v65, v65
	v_mul_f32_e32 v67, 0xbfb8aa3b, v111
	v_exp_f32_e32 v67, v67
	s_nop 0
	v_pk_mul_f32 v[94:95], v[106:107], v[94:95]
	v_add_f32_e32 v65, 1.0, v65
	v_rcp_f32_e32 v112, v65
	v_add_f32_e32 v65, 1.0, v67
	v_rcp_f32_e32 v113, v65
	v_pk_mul_f32 v[96:97], v[96:97], v[102:103]
	v_lshlrev_b32_e32 v102, 16, v92
	v_and_b32_e32 v103, 0xffff0000, v92
	v_pk_mul_f32 v[106:107], v[112:113], v[110:111]
	v_lshlrev_b32_e32 v110, 16, v91
	v_and_b32_e32 v111, 0xffff0000, v91
	v_mul_f32_e32 v65, 0xbfb8aa3b, v110
	v_exp_f32_e32 v65, v65
	v_mul_f32_e32 v67, 0xbfb8aa3b, v111
	v_exp_f32_e32 v67, v67
	v_pk_mul_f32 v[90:91], v[94:95], v[106:107]
	v_add_f32_e32 v65, 1.0, v65
	v_rcp_f32_e32 v94, v65
	v_add_f32_e32 v65, 1.0, v67
	v_rcp_f32_e32 v95, v65
	v_mul_f32_e32 v65, 0xbfb8aa3b, v102
	v_exp_f32_e32 v65, v65
	v_mul_f32_e32 v67, 0xbfb8aa3b, v103
	v_exp_f32_e32 v67, v67
	v_pk_mul_f32 v[94:95], v[94:95], v[110:111]
	v_cvt_pk_bf16_f32 v90, v90, v91
	v_pk_mul_f32 v[94:95], v[96:97], v[94:95]
	v_add_f32_e32 v65, 1.0, v65
	v_cvt_pk_bf16_f32 v91, v94, v95
	v_pk_mul_f32 v[94:95], v[68:69], v[108:109] op_sel_hi:[0,1]
	v_rcp_f32_e32 v96, v65
	v_add_f32_e32 v65, 1.0, v67
	s_nop 0
	v_pk_mul_f32 v[94:95], v[94:95], v[98:99]
	v_lshlrev_b32_e32 v98, 16, v93
	v_rcp_f32_e32 v97, v65
	v_and_b32_e32 v99, 0xffff0000, v93
	v_mul_f32_e32 v65, 0xbfb8aa3b, v98
	v_exp_f32_e32 v65, v65
	v_mul_f32_e32 v67, 0xbfb8aa3b, v99
	v_exp_f32_e32 v67, v67
	v_pk_mul_f32 v[96:97], v[96:97], v[102:103]
	v_add_f32_e32 v65, 1.0, v65
	v_pk_mul_f32 v[92:93], v[94:95], v[96:97]
	v_rcp_f32_e32 v94, v65
	v_add_f32_e32 v65, 1.0, v67
	v_rcp_f32_e32 v95, v65
	v_pk_mul_f32 v[96:97], v[68:69], v[104:105] op_sel_hi:[0,1]
	v_pk_mul_f32 v[96:97], v[96:97], v[100:101]
	v_cvt_pk_bf16_f32 v92, v92, v93
	v_pk_mul_f32 v[94:95], v[94:95], v[98:99]
	v_pk_mul_f32 v[86:87], v[86:87], v[66:67] op_sel_hi:[1,0]
	v_pk_mul_f32 v[94:95], v[96:97], v[94:95]
	v_pk_mul_f32 v[88:89], v[88:89], v[66:67] op_sel_hi:[1,0]
	v_cvt_pk_bf16_f32 v93, v94, v95
	global_store_dwordx4 v[186:187], v[90:93], off offset:128
	s_nop 1
	v_mov_b32_e32 v90, v136
	v_mov_b32_e32 v91, v137
	v_mov_b32_e32 v92, v138
	v_mov_b32_e32 v93, v139
	ds_read_b128 v[94:97], v251 offset:320
	ds_read_b128 v[98:101], v251 offset:336
	ds_read2st64_b32 v[102:103], v210 offset0:244 offset1:245
	ds_read2st64_b32 v[104:105], v210 offset0:246 offset1:247
	s_waitcnt lgkmcnt(1)
	v_lshlrev_b32_e32 v65, 16, v102
	v_fma_f32 v106, -v24, v66, v65
	v_and_b32_e32 v65, 0xffff0000, v102
	v_fma_f32 v107, -v25, v66, v65
	s_waitcnt lgkmcnt(0)
	v_lshlrev_b32_e32 v65, 16, v104
	v_sub_f32_e32 v108, v65, v86
	v_and_b32_e32 v65, 0xffff0000, v104
	v_sub_f32_e32 v109, v65, v88
	v_lshlrev_b32_e32 v65, 16, v103
	v_fma_f32 v102, -v26, v66, v65
	v_and_b32_e32 v65, 0xffff0000, v103
	v_fma_f32 v103, -v27, v66, v65
	v_lshlrev_b32_e32 v65, 16, v105
	v_sub_f32_e32 v104, v65, v87
	v_and_b32_e32 v65, 0xffff0000, v105
	v_sub_f32_e32 v105, v65, v89
	v_permlane32_swap_b32_e32 v106, v108
	v_permlane32_swap_b32_e32 v107, v109
	v_pk_mul_f32 v[106:107], v[68:69], v[106:107] op_sel_hi:[0,1]
	v_permlane32_swap_b32_e32 v102, v104
	v_permlane32_swap_b32_e32 v103, v105
	s_nop 0
	v_lshlrev_b32_e32 v86, 16, v90
	v_and_b32_e32 v87, 0xffff0000, v90
	v_mul_f32_e32 v65, 0xbfb8aa3b, v86
	v_exp_f32_e32 v65, v65
	v_mul_f32_e32 v67, 0xbfb8aa3b, v87
	v_exp_f32_e32 v67, v67
	s_nop 0
	v_pk_mul_f32 v[94:95], v[106:107], v[94:95]
	v_add_f32_e32 v65, 1.0, v65
	v_rcp_f32_e32 v88, v65
	v_add_f32_e32 v65, 1.0, v67
	v_rcp_f32_e32 v89, v65
	s_nop 0
	v_pk_mul_f32 v[86:87], v[88:89], v[86:87]
	v_lshlrev_b32_e32 v88, 16, v91
	v_and_b32_e32 v89, 0xffff0000, v91
	v_mul_f32_e32 v65, 0xbfb8aa3b, v88
	v_exp_f32_e32 v65, v65
	v_mul_f32_e32 v67, 0xbfb8aa3b, v89
	v_exp_f32_e32 v67, v67
	v_pk_mul_f32 v[86:87], v[94:95], v[86:87]
	v_add_f32_e32 v65, 1.0, v65
	v_rcp_f32_e32 v90, v65
	v_add_f32_e32 v65, 1.0, v67
	v_rcp_f32_e32 v91, v65
	v_pk_mul_f32 v[94:95], v[68:69], v[102:103] op_sel_hi:[0,1]
	v_pk_mul_f32 v[94:95], v[96:97], v[94:95]
	v_cvt_pk_bf16_f32 v86, v86, v87
	v_pk_mul_f32 v[88:89], v[90:91], v[88:89]
	v_lshlrev_b32_e32 v90, 16, v92
	v_and_b32_e32 v91, 0xffff0000, v92
	v_mul_f32_e32 v65, 0xbfb8aa3b, v90
	v_exp_f32_e32 v65, v65
	v_mul_f32_e32 v67, 0xbfb8aa3b, v91
	v_exp_f32_e32 v67, v67
	v_pk_mul_f32 v[88:89], v[94:95], v[88:89]
	v_add_f32_e32 v65, 1.0, v65
	v_rcp_f32_e32 v94, v65
	v_add_f32_e32 v65, 1.0, v67
	v_lshlrev_b32_e32 v92, 16, v93
	v_rcp_f32_e32 v95, v65
	v_and_b32_e32 v93, 0xffff0000, v93
	v_mul_f32_e32 v65, 0xbfb8aa3b, v92
	v_exp_f32_e32 v65, v65
	v_mul_f32_e32 v67, 0xbfb8aa3b, v93
	v_exp_f32_e32 v67, v67
	v_cvt_pk_bf16_f32 v87, v88, v89
	v_pk_mul_f32 v[88:89], v[68:69], v[108:109] op_sel_hi:[0,1]
	s_nop 0
	v_pk_mul_f32 v[88:89], v[88:89], v[98:99]
	v_pk_mul_f32 v[90:91], v[94:95], v[90:91]
	v_add_f32_e32 v65, 1.0, v65
	v_pk_mul_f32 v[88:89], v[88:89], v[90:91]
	v_rcp_f32_e32 v90, v65
	v_add_f32_e32 v65, 1.0, v67
	v_rcp_f32_e32 v91, v65
	v_pk_mul_f32 v[94:95], v[68:69], v[104:105] op_sel_hi:[0,1]
	v_pk_mul_f32 v[94:95], v[94:95], v[100:101]
	v_cvt_pk_bf16_f32 v88, v88, v89
	v_pk_mul_f32 v[90:91], v[90:91], v[92:93]
	v_pk_mul_f32 v[78:79], v[78:79], v[66:67] op_sel_hi:[1,0]
	v_pk_mul_f32 v[90:91], v[94:95], v[90:91]
	v_pk_mul_f32 v[80:81], v[80:81], v[66:67] op_sel_hi:[1,0]
	v_cvt_pk_bf16_f32 v89, v90, v91
	global_store_dwordx4 v[186:187], v[86:89], off offset:160
	s_nop 1
	v_mov_b32_e32 v86, v140
	v_mov_b32_e32 v87, v141
	v_mov_b32_e32 v88, v142
	v_mov_b32_e32 v89, v143
	ds_read_b128 v[90:93], v251 offset:384
	ds_read_b128 v[94:97], v251 offset:400
	ds_read2st64_b32 v[98:99], v210 offset0:248 offset1:249
	ds_read2st64_b32 v[100:101], v210 offset0:250 offset1:251
	v_pk_mul_f32 v[82:83], v[82:83], v[66:67] op_sel_hi:[1,0]
	v_pk_mul_f32 v[84:85], v[84:85], v[66:67] op_sel_hi:[1,0]
	s_waitcnt lgkmcnt(1)
	v_lshlrev_b32_e32 v65, 16, v98
	v_sub_f32_e32 v102, v65, v78
	v_and_b32_e32 v65, 0xffff0000, v98
	v_sub_f32_e32 v103, v65, v80
	s_waitcnt lgkmcnt(0)
	v_lshlrev_b32_e32 v65, 16, v100
	v_sub_f32_e32 v104, v65, v82
	v_and_b32_e32 v65, 0xffff0000, v100
	v_sub_f32_e32 v105, v65, v84
	v_lshlrev_b32_e32 v65, 16, v99
	v_sub_f32_e32 v80, v65, v79
	v_and_b32_e32 v65, 0xffff0000, v99
	v_sub_f32_e32 v81, v65, v81
	v_lshlrev_b32_e32 v65, 16, v101
	v_sub_f32_e32 v82, v65, v83
	v_and_b32_e32 v65, 0xffff0000, v101
	v_sub_f32_e32 v83, v65, v85
	v_permlane32_swap_b32_e32 v80, v82
	s_nop 0
	v_permlane32_swap_b32_e32 v81, v83
	v_pk_mul_f32 v[80:81], v[68:69], v[80:81] op_sel_hi:[0,1]
	v_permlane32_swap_b32_e32 v102, v104
	v_permlane32_swap_b32_e32 v103, v105
	v_pk_mul_f32 v[98:99], v[68:69], v[102:103] op_sel_hi:[0,1]
	v_pk_mul_f32 v[82:83], v[68:69], v[82:83] op_sel_hi:[0,1]
	s_nop 0
	v_lshlrev_b32_e32 v78, 16, v86
	v_and_b32_e32 v79, 0xffff0000, v86
	v_mul_f32_e32 v65, 0xbfb8aa3b, v78
	v_exp_f32_e32 v65, v65
	v_mul_f32_e32 v67, 0xbfb8aa3b, v79
	v_exp_f32_e32 v67, v67
	s_nop 0
	v_pk_mul_f32 v[80:81], v[92:93], v[80:81]
	v_add_f32_e32 v65, 1.0, v65
	v_rcp_f32_e32 v84, v65
	v_add_f32_e32 v65, 1.0, v67
	v_rcp_f32_e32 v85, v65
	v_pk_mul_f32 v[90:91], v[98:99], v[90:91]
	s_nop 0
	v_pk_mul_f32 v[82:83], v[82:83], v[96:97]
	v_pk_mul_f32 v[78:79], v[84:85], v[78:79]
	v_lshlrev_b32_e32 v84, 16, v87
	v_and_b32_e32 v85, 0xffff0000, v87
	v_mul_f32_e32 v65, 0xbfb8aa3b, v84
	v_exp_f32_e32 v65, v65
	v_mul_f32_e32 v67, 0xbfb8aa3b, v85
	v_exp_f32_e32 v67, v67
	v_pk_mul_f32 v[78:79], v[90:91], v[78:79]
	v_add_f32_e32 v65, 1.0, v65
	v_rcp_f32_e32 v86, v65
	v_add_f32_e32 v65, 1.0, v67
	v_rcp_f32_e32 v87, v65
	v_cvt_pk_bf16_f32 v78, v78, v79
	v_pk_mul_f32 v[84:85], v[86:87], v[84:85]
	v_lshlrev_b32_e32 v86, 16, v88
	v_and_b32_e32 v87, 0xffff0000, v88
	v_mul_f32_e32 v65, 0xbfb8aa3b, v86
	v_exp_f32_e32 v65, v65
	v_mul_f32_e32 v67, 0xbfb8aa3b, v87
	v_exp_f32_e32 v67, v67
	v_pk_mul_f32 v[80:81], v[80:81], v[84:85]
	v_add_f32_e32 v65, 1.0, v65
	v_rcp_f32_e32 v84, v65
	v_add_f32_e32 v65, 1.0, v67
	v_rcp_f32_e32 v85, v65
	v_cvt_pk_bf16_f32 v79, v80, v81
	v_pk_mul_f32 v[80:81], v[68:69], v[104:105] op_sel_hi:[0,1]
	v_pk_mul_f32 v[80:81], v[80:81], v[94:95]
	v_pk_mul_f32 v[84:85], v[84:85], v[86:87]
	v_lshlrev_b32_e32 v86, 16, v89
	v_and_b32_e32 v87, 0xffff0000, v89
	v_mul_f32_e32 v65, 0xbfb8aa3b, v86
	v_exp_f32_e32 v65, v65
	v_mul_f32_e32 v67, 0xbfb8aa3b, v87
	v_exp_f32_e32 v67, v67
	v_pk_mul_f32 v[80:81], v[80:81], v[84:85]
	v_add_f32_e32 v65, 1.0, v65
	v_rcp_f32_e32 v84, v65
	v_add_f32_e32 v65, 1.0, v67
	v_rcp_f32_e32 v85, v65
	v_cvt_pk_bf16_f32 v80, v80, v81
	v_pk_mul_f32 v[70:71], v[70:71], v[66:67] op_sel_hi:[1,0]
	v_pk_mul_f32 v[72:73], v[72:73], v[66:67] op_sel_hi:[1,0]
	v_pk_mul_f32 v[84:85], v[84:85], v[86:87]
	v_pk_mul_f32 v[74:75], v[74:75], v[66:67] op_sel_hi:[1,0]
	v_pk_mul_f32 v[82:83], v[82:83], v[84:85]
	v_pk_mul_f32 v[66:67], v[76:77], v[66:67] op_sel_hi:[1,0]
	v_cvt_pk_bf16_f32 v81, v82, v83
	global_store_dwordx4 v[186:187], v[78:81], off offset:192
	s_nop 1
	v_mov_b32_e32 v78, v144
	v_mov_b32_e32 v79, v145
	v_mov_b32_e32 v80, v146
	v_mov_b32_e32 v81, v147
	ds_read_b128 v[82:85], v251 offset:448
	ds_read_b128 v[86:89], v251 offset:464
	ds_read2st64_b32 v[90:91], v210 offset0:252 offset1:253
	ds_read2st64_b32 v[76:77], v210 offset0:254 offset1:255
	s_waitcnt lgkmcnt(1)
	v_lshlrev_b32_e32 v65, 16, v90
	v_sub_f32_e32 v92, v65, v70
	v_and_b32_e32 v65, 0xffff0000, v90
	v_sub_f32_e32 v93, v65, v72
	s_waitcnt lgkmcnt(0)
	v_lshlrev_b32_e32 v65, 16, v76
	v_sub_f32_e32 v94, v65, v74
	v_and_b32_e32 v65, 0xffff0000, v76
	v_sub_f32_e32 v95, v65, v66
	v_lshlrev_b32_e32 v65, 16, v91
	v_sub_f32_e32 v72, v65, v71
	v_and_b32_e32 v65, 0xffff0000, v91
	v_sub_f32_e32 v73, v65, v73
	v_lshlrev_b32_e32 v65, 16, v77
	v_sub_f32_e32 v66, v65, v75
	v_and_b32_e32 v65, 0xffff0000, v77
	v_sub_f32_e32 v67, v65, v67
	v_permlane32_swap_b32_e32 v92, v94
	v_permlane32_swap_b32_e32 v93, v95
	v_permlane32_swap_b32_e32 v72, v66
	v_permlane32_swap_b32_e32 v73, v67
	s_nop 0
	v_lshlrev_b32_e32 v70, 16, v78
	v_and_b32_e32 v71, 0xffff0000, v78
	v_mul_f32_e32 v65, 0xbfb8aa3b, v70
	v_exp_f32_e32 v65, v65
	v_mul_f32_e32 v69, 0xbfb8aa3b, v71
	v_exp_f32_e32 v69, v69
	v_add_f32_e32 v65, 1.0, v65
	v_rcp_f32_e32 v74, v65
	v_add_f32_e32 v65, 1.0, v69
	v_rcp_f32_e32 v75, v65
	v_pk_mul_f32 v[76:77], v[68:69], v[92:93] op_sel_hi:[0,1]
	s_nop 0
	v_pk_mul_f32 v[76:77], v[76:77], v[82:83]
	v_pk_mul_f32 v[70:71], v[74:75], v[70:71]
	v_lshlrev_b32_e32 v74, 16, v79
	v_and_b32_e32 v75, 0xffff0000, v79
	v_mul_f32_e32 v65, 0xbfb8aa3b, v74
	v_exp_f32_e32 v65, v65
	v_mul_f32_e32 v69, 0xbfb8aa3b, v75
	v_exp_f32_e32 v69, v69
	v_pk_mul_f32 v[70:71], v[76:77], v[70:71]
	v_add_f32_e32 v65, 1.0, v65
	v_rcp_f32_e32 v76, v65
	v_add_f32_e32 v65, 1.0, v69
	v_rcp_f32_e32 v77, v65
	v_pk_mul_f32 v[72:73], v[68:69], v[72:73] op_sel_hi:[0,1]
	v_pk_mul_f32 v[72:73], v[84:85], v[72:73]
	v_cvt_pk_bf16_f32 v70, v70, v71
	v_pk_mul_f32 v[74:75], v[76:77], v[74:75]
	v_lshlrev_b32_e32 v76, 16, v80
	v_and_b32_e32 v77, 0xffff0000, v80
	v_mul_f32_e32 v65, 0xbfb8aa3b, v76
	v_exp_f32_e32 v65, v65
	v_mul_f32_e32 v69, 0xbfb8aa3b, v77
	v_exp_f32_e32 v69, v69
	v_pk_mul_f32 v[72:73], v[72:73], v[74:75]
	v_add_f32_e32 v65, 1.0, v65
	v_rcp_f32_e32 v74, v65
	v_add_f32_e32 v65, 1.0, v69
	v_rcp_f32_e32 v75, v65
	v_cvt_pk_bf16_f32 v71, v72, v73
	v_pk_mul_f32 v[72:73], v[68:69], v[94:95] op_sel_hi:[0,1]
	s_nop 0
	v_pk_mul_f32 v[72:73], v[72:73], v[86:87]
	v_pk_mul_f32 v[74:75], v[74:75], v[76:77]
	v_lshlrev_b32_e32 v76, 16, v81
	v_and_b32_e32 v77, 0xffff0000, v81
	v_mul_f32_e32 v65, 0xbfb8aa3b, v76
	v_exp_f32_e32 v65, v65
	v_mul_f32_e32 v69, 0xbfb8aa3b, v77
	v_exp_f32_e32 v69, v69
	v_pk_mul_f32 v[72:73], v[72:73], v[74:75]
	v_add_f32_e32 v65, 1.0, v65
	v_rcp_f32_e32 v74, v65
	v_add_f32_e32 v65, 1.0, v69
	v_rcp_f32_e32 v75, v65
	v_pk_mul_f32 v[66:67], v[68:69], v[66:67] op_sel_hi:[0,1]
	v_pk_mul_f32 v[66:67], v[66:67], v[88:89]
	v_cvt_pk_bf16_f32 v72, v72, v73
	v_pk_mul_f32 v[68:69], v[74:75], v[76:77]
	s_nop 0
	v_pk_mul_f32 v[66:67], v[66:67], v[68:69]
	s_nop 0
	v_cvt_pk_bf16_f32 v73, v66, v67
	global_store_dwordx4 v[186:187], v[70:73], off offset:224
	s_cbranch_execnz .LBB0_420
	s_branch .LBB0_435
